# instruction selection: the 65 f32 IEEE division sequences in the SiLU gates (attention epilogue, post phase) replaced by v_rcp_f32 + multiply (f32 throughout, results are rounded to bf16 right after)
# speedup vs baseline: 1.0075x; 1.0054x over previous
.LBB0_152:
	v_and_b32_e32 v29, 64, v181
	v_readlane_b32 s0, v254, 26
	v_xor_b32_e32 v28, 16, v181
	v_add_u32_e32 v29, 64, v29
	v_readlane_b32 s1, v254, 27
	v_cmp_lt_i32_e32 vcc, v28, v29
	v_xor_b32_e32 v30, 32, v181
	s_mov_b32 s1, s47
	v_cndmask_b32_e32 v28, v181, v28, vcc
	v_cmp_lt_i32_e32 vcc, v30, v29
	s_lshl_b64 s[0:1], s[0:1], 1
	v_readlane_b32 s4, v253, 33
	v_cndmask_b32_e32 v29, v181, v30, vcc
	v_lshl_add_u64 v[30:31], v[126:127], 0, s[0:1]
	v_readlane_b32 s5, v253, 34
	s_add_u32 s0, s4, s0
	s_addc_u32 s1, s5, s1
	v_mov_b64_e32 v[32:33], s[0:1]
	v_mad_i64_i32 v[34:35], s[0:1], v204, s70, v[32:33]
	v_lshlrev_b32_e32 v144, 1, v122
	v_lshl_add_u64 v[32:33], v[30:31], 0, v[144:145]
	s_mov_b64 s[0:1], 0x2400
	v_lshl_add_u64 v[30:31], v[32:33], 0, s[0:1]
	s_movk_i32 s0, 0x2000
	v_add_co_u32_e32 v32, vcc, s0, v32
	v_lshlrev_b32_e32 v28, 2, v28
	s_nop 0
	v_addc_co_u32_e32 v33, vcc, 0, v33, vcc
	global_load_dwordx2 v[32:33], v[32:33], off offset:1024 nt
	global_load_dwordx2 v[0:1], v[30:31], off offset:32 nt
	global_load_dwordx2 v[2:3], v[30:31], off offset:64 nt
	global_load_dwordx2 v[4:5], v[30:31], off offset:96 nt
	global_load_dwordx2 v[6:7], v[30:31], off offset:128 nt
	global_load_dwordx2 v[8:9], v[30:31], off offset:160 nt
	global_load_dwordx2 v[10:11], v[30:31], off offset:192 nt
	global_load_dwordx2 v[12:13], v[30:31], off offset:224 nt
	ds_bpermute_b32 v28, v28, v205
	v_lshlrev_b32_e32 v29, 2, v29
	v_readlane_b32 s96, v254, 21
	v_readlane_b32 s97, v254, 22
	v_readlane_b32 s98, v254, 24
	s_waitcnt lgkmcnt(0)
	v_add_f32_e32 v28, v205, v28
	ds_bpermute_b32 v146, v29, v28
	v_readlane_b32 s99, v254, 23
	v_readlane_b32 s97, v254, 25
	s_mov_b64 s[38:39], 0
	s_waitcnt vmcnt(0)
	v_lshlrev_b32_e32 v29, 16, v32
	v_mul_f32_e32 v37, 0xbfb8aa3b, v29
	v_exp_f32_e32 v37, v37
	v_and_b32_e32 v32, 0xffff0000, v32
	v_lshlrev_b32_e32 v36, 16, v33
	v_and_b32_e32 v33, 0xffff0000, v33
	v_add_f32_e32 v37, 1.0, v37
	s_nop 0
	v_rcp_f32_e32 v38, v37
	s_nop 0
	v_mul_f32_e32 v37, v29, v38
	v_mul_f32_e32 v29, 0xbfb8aa3b, v32
	v_exp_f32_e32 v29, v29
	s_nop 0
	v_add_f32_e32 v29, 1.0, v29
	s_nop 0
	v_rcp_f32_e32 v38, v29
	s_nop 0
	v_mul_f32_e32 v38, v32, v38
	v_mul_f32_e32 v29, 0xbfb8aa3b, v36
	v_exp_f32_e32 v29, v29
	s_waitcnt lgkmcnt(0)
	v_pk_add_f32 v[28:29], v[28:29], v[146:147]
	s_nop 0
	s_nop 0
	v_rcp_f32_e32 v32, v29
	s_nop 0
	v_mul_f32_e32 v29, v36, v32
	s_nop 0
	v_rcp_f32_e32 v32, v28
	s_nop 0
	v_mul_f32_e32 v32, 1.0, v32
	v_mul_f32_e32 v28, v76, v32
	v_mul_f32_e32 v28, v28, v37
	v_mul_f32_e32 v37, 0xbfb8aa3b, v33
	v_exp_f32_e32 v37, v37
	v_mul_f32_e32 v36, v77, v32
	v_mul_f32_e32 v36, v36, v38
	v_cvt_pk_bf16_f32 v36, v28, v36
	v_add_f32_e32 v37, 1.0, v37
	v_mul_f32_e32 v28, v78, v32
	v_mul_f32_e32 v28, v28, v29
	v_mul_f32_e32 v29, v79, v32
	v_rcp_f32_e32 v38, v37
	s_nop 0
	v_mul_f32_e32 v33, v33, v38
	v_mul_f32_e32 v29, v29, v33
	v_cvt_pk_bf16_f32 v37, v28, v29
	v_lshl_add_u64 v[28:29], v[34:35], 0, v[144:145]
	v_mov_b64_e32 v[34:35], v[0:1]
	v_mul_f32_e32 v24, v24, v32
	global_store_dwordx2 v[28:29], v[36:37], off
	v_mul_f32_e32 v37, v72, v32
	v_mul_f32_e32 v25, v25, v32
	v_mul_f32_e32 v20, v20, v32
	v_mul_f32_e32 v21, v21, v32
	v_mul_f32_e32 v16, v16, v32
	v_mul_f32_e32 v17, v17, v32
	v_lshlrev_b32_e32 v33, 16, v34
	v_mul_f32_e32 v38, 0xbfb8aa3b, v33
	v_exp_f32_e32 v38, v38
	v_and_b32_e32 v34, 0xffff0000, v34
	v_lshlrev_b32_e32 v36, 16, v35
	v_and_b32_e32 v35, 0xffff0000, v35
	v_add_f32_e32 v38, 1.0, v38
	s_nop 0
	v_rcp_f32_e32 v39, v38
	s_nop 0
	v_mul_f32_e32 v33, v33, v39
	v_mul_f32_e32 v38, 0xbfb8aa3b, v34
	v_exp_f32_e32 v38, v38
	v_mul_f32_e32 v33, v37, v33
	v_mul_f32_e32 v37, v73, v32
	v_add_f32_e32 v38, 1.0, v38
	s_nop 0
	v_rcp_f32_e32 v39, v38
	s_nop 0
	v_mul_f32_e32 v34, v34, v39
	v_mul_f32_e32 v34, v37, v34
	v_mul_f32_e32 v37, 0xbfb8aa3b, v36
	v_exp_f32_e32 v37, v37
	v_cvt_pk_bf16_f32 v34, v33, v34
	v_mul_f32_e32 v33, v74, v32
	v_add_f32_e32 v37, 1.0, v37
	s_nop 0
	v_rcp_f32_e32 v38, v37
	s_nop 0
	v_mul_f32_e32 v36, v36, v38
	v_mul_f32_e32 v37, 0xbfb8aa3b, v35
	v_exp_f32_e32 v37, v37
	v_mul_f32_e32 v33, v33, v36
	v_mul_f32_e32 v36, v75, v32
	v_add_f32_e32 v37, 1.0, v37
	s_nop 0
	v_rcp_f32_e32 v38, v37
	s_nop 0
	v_mul_f32_e32 v35, v35, v38
	v_mul_f32_e32 v35, v36, v35
	v_cvt_pk_bf16_f32 v35, v33, v35
	global_store_dwordx2 v[28:29], v[34:35], off offset:32
	v_mov_b64_e32 v[34:35], v[2:3]
	v_mul_f32_e32 v37, v68, v32
	v_lshlrev_b32_e32 v33, 16, v34
	v_mul_f32_e32 v38, 0xbfb8aa3b, v33
	v_exp_f32_e32 v38, v38
	v_and_b32_e32 v34, 0xffff0000, v34
	v_lshlrev_b32_e32 v36, 16, v35
	v_and_b32_e32 v35, 0xffff0000, v35
	v_add_f32_e32 v38, 1.0, v38
	s_nop 0
	v_rcp_f32_e32 v39, v38
	s_nop 0
	v_mul_f32_e32 v33, v33, v39
	v_mul_f32_e32 v38, 0xbfb8aa3b, v34
	v_exp_f32_e32 v38, v38
	v_mul_f32_e32 v33, v37, v33
	v_mul_f32_e32 v37, v69, v32
	v_add_f32_e32 v38, 1.0, v38
	s_nop 0
	v_rcp_f32_e32 v39, v38
	s_nop 0
	v_mul_f32_e32 v34, v34, v39
	v_mul_f32_e32 v34, v37, v34
	v_mul_f32_e32 v37, 0xbfb8aa3b, v36
	v_exp_f32_e32 v37, v37
	v_cvt_pk_bf16_f32 v34, v33, v34
	v_mul_f32_e32 v33, v70, v32
	v_add_f32_e32 v37, 1.0, v37
	s_nop 0
	v_rcp_f32_e32 v38, v37
	s_nop 0
	v_mul_f32_e32 v36, v36, v38
	v_mul_f32_e32 v37, 0xbfb8aa3b, v35
	v_exp_f32_e32 v37, v37
	v_mul_f32_e32 v33, v33, v36
	v_mul_f32_e32 v36, v71, v32
	v_add_f32_e32 v37, 1.0, v37
	s_nop 0
	v_rcp_f32_e32 v38, v37
	s_nop 0
	v_mul_f32_e32 v35, v35, v38
	v_mul_f32_e32 v35, v36, v35
	v_cvt_pk_bf16_f32 v35, v33, v35
	global_store_dwordx2 v[28:29], v[34:35], off offset:64
	v_mov_b64_e32 v[34:35], v[4:5]
	v_mul_f32_e32 v37, v64, v32
	v_lshlrev_b32_e32 v33, 16, v34
	v_mul_f32_e32 v38, 0xbfb8aa3b, v33
	v_exp_f32_e32 v38, v38
	v_and_b32_e32 v34, 0xffff0000, v34
	v_lshlrev_b32_e32 v36, 16, v35
	v_and_b32_e32 v35, 0xffff0000, v35
	v_add_f32_e32 v38, 1.0, v38
	s_nop 0
	v_rcp_f32_e32 v39, v38
	s_nop 0
	v_mul_f32_e32 v33, v33, v39
	v_mul_f32_e32 v38, 0xbfb8aa3b, v34
	v_exp_f32_e32 v38, v38
	v_mul_f32_e32 v33, v37, v33
	v_mul_f32_e32 v37, v65, v32
	v_add_f32_e32 v38, 1.0, v38
	s_nop 0
	v_rcp_f32_e32 v39, v38
	s_nop 0
	v_mul_f32_e32 v34, v34, v39
	v_mul_f32_e32 v34, v37, v34
	v_mul_f32_e32 v37, 0xbfb8aa3b, v36
	v_exp_f32_e32 v37, v37
	v_cvt_pk_bf16_f32 v34, v33, v34
	v_mul_f32_e32 v33, v66, v32
	v_add_f32_e32 v37, 1.0, v37
	s_nop 0
	v_rcp_f32_e32 v38, v37
	s_nop 0
	v_mul_f32_e32 v36, v36, v38
	v_mul_f32_e32 v37, 0xbfb8aa3b, v35
	v_exp_f32_e32 v37, v37
	v_mul_f32_e32 v33, v33, v36
	v_mul_f32_e32 v36, v67, v32
	v_add_f32_e32 v37, 1.0, v37
	s_nop 0
	v_rcp_f32_e32 v38, v37
	s_nop 0
	v_mul_f32_e32 v35, v35, v38
	v_mul_f32_e32 v35, v36, v35
	v_cvt_pk_bf16_f32 v35, v33, v35
	global_store_dwordx2 v[28:29], v[34:35], off offset:96
	v_mov_b64_e32 v[34:35], v[6:7]
	v_mul_f32_e32 v37, v60, v32
	v_lshlrev_b32_e32 v33, 16, v34
	v_mul_f32_e32 v38, 0xbfb8aa3b, v33
	v_exp_f32_e32 v38, v38
	v_and_b32_e32 v34, 0xffff0000, v34
	v_lshlrev_b32_e32 v36, 16, v35
	v_and_b32_e32 v35, 0xffff0000, v35
	v_add_f32_e32 v38, 1.0, v38
	s_nop 0
	v_rcp_f32_e32 v39, v38
	s_nop 0
	v_mul_f32_e32 v33, v33, v39
	v_mul_f32_e32 v38, 0xbfb8aa3b, v34
	v_exp_f32_e32 v38, v38
	v_mul_f32_e32 v33, v37, v33
	v_mul_f32_e32 v37, v61, v32
	v_add_f32_e32 v38, 1.0, v38
	s_nop 0
	v_rcp_f32_e32 v39, v38
	s_nop 0
	v_mul_f32_e32 v34, v34, v39
	v_mul_f32_e32 v34, v37, v34
	v_mul_f32_e32 v37, 0xbfb8aa3b, v36
	v_exp_f32_e32 v37, v37
	v_cvt_pk_bf16_f32 v34, v33, v34
	v_mul_f32_e32 v33, v62, v32
	v_add_f32_e32 v37, 1.0, v37
	s_nop 0
	v_rcp_f32_e32 v38, v37
	s_nop 0
	v_mul_f32_e32 v36, v36, v38
	v_mul_f32_e32 v37, 0xbfb8aa3b, v35
	v_exp_f32_e32 v37, v37
	v_mul_f32_e32 v33, v33, v36
	v_mul_f32_e32 v36, v63, v32
	v_add_f32_e32 v37, 1.0, v37
	s_nop 0
	v_rcp_f32_e32 v38, v37
	s_nop 0
	v_mul_f32_e32 v35, v35, v38
	v_mul_f32_e32 v35, v36, v35
	v_cvt_pk_bf16_f32 v35, v33, v35
	global_store_dwordx2 v[28:29], v[34:35], off offset:128
	v_mov_b64_e32 v[34:35], v[8:9]
	v_lshlrev_b32_e32 v33, 16, v34
	v_mul_f32_e32 v37, 0xbfb8aa3b, v33
	v_exp_f32_e32 v37, v37
	v_and_b32_e32 v34, 0xffff0000, v34
	v_lshlrev_b32_e32 v36, 16, v35
	v_and_b32_e32 v35, 0xffff0000, v35
	v_add_f32_e32 v37, 1.0, v37
	s_nop 0
	v_rcp_f32_e32 v38, v37
	s_nop 0
	v_mul_f32_e32 v33, v33, v38
	v_mul_f32_e32 v24, v24, v33
	v_mul_f32_e32 v33, 0xbfb8aa3b, v34
	v_exp_f32_e32 v33, v33
	s_nop 0
	v_add_f32_e32 v33, 1.0, v33
	s_nop 0
	v_rcp_f32_e32 v37, v33
	s_nop 0
	v_mul_f32_e32 v33, v34, v37
	v_mul_f32_e32 v25, v25, v33
	v_cvt_pk_bf16_f32 v24, v24, v25
	v_mul_f32_e32 v25, v26, v32
	v_mul_f32_e32 v26, 0xbfb8aa3b, v36
	v_exp_f32_e32 v26, v26
	s_nop 0
	v_add_f32_e32 v26, 1.0, v26
	s_nop 0
	v_rcp_f32_e32 v33, v26
	s_nop 0
	v_mul_f32_e32 v26, v36, v33
	v_mul_f32_e32 v25, v25, v26
	v_mul_f32_e32 v26, v27, v32
	v_mul_f32_e32 v27, 0xbfb8aa3b, v35
	v_exp_f32_e32 v27, v27
	s_nop 0
	v_add_f32_e32 v27, 1.0, v27
	s_nop 0
	v_rcp_f32_e32 v33, v27
	s_nop 0
	v_mul_f32_e32 v27, v35, v33
	v_mul_f32_e32 v26, v26, v27
	v_cvt_pk_bf16_f32 v25, v25, v26
	global_store_dwordx2 v[28:29], v[24:25], off offset:160
	v_mov_b64_e32 v[24:25], v[10:11]
	v_lshlrev_b32_e32 v26, 16, v24
	v_mul_f32_e32 v33, 0xbfb8aa3b, v26
	v_exp_f32_e32 v33, v33
	v_and_b32_e32 v24, 0xffff0000, v24
	v_lshlrev_b32_e32 v27, 16, v25
	v_and_b32_e32 v25, 0xffff0000, v25
	v_add_f32_e32 v33, 1.0, v33
	s_nop 0
	v_rcp_f32_e32 v34, v33
	s_nop 0
	v_mul_f32_e32 v26, v26, v34
	v_mul_f32_e32 v20, v20, v26
	v_mul_f32_e32 v26, 0xbfb8aa3b, v24
	v_exp_f32_e32 v26, v26
	s_nop 0
	v_add_f32_e32 v26, 1.0, v26
	s_nop 0
	v_rcp_f32_e32 v33, v26
	s_nop 0
	v_mul_f32_e32 v24, v24, v33
	v_mul_f32_e32 v21, v21, v24
	v_cvt_pk_bf16_f32 v20, v20, v21
	v_mul_f32_e32 v21, v22, v32
	v_mul_f32_e32 v22, 0xbfb8aa3b, v27
	v_exp_f32_e32 v22, v22
	s_nop 0
	v_add_f32_e32 v22, 1.0, v22
	s_nop 0
	v_rcp_f32_e32 v24, v22
	s_nop 0
	v_mul_f32_e32 v22, v27, v24
	v_mul_f32_e32 v21, v21, v22
	v_mul_f32_e32 v22, v23, v32
	v_mul_f32_e32 v23, 0xbfb8aa3b, v25
	v_exp_f32_e32 v23, v23
	s_nop 0
	v_add_f32_e32 v23, 1.0, v23
	s_nop 0
	v_rcp_f32_e32 v24, v23
	s_nop 0
	v_mul_f32_e32 v23, v25, v24
	v_mul_f32_e32 v22, v22, v23
	v_cvt_pk_bf16_f32 v21, v21, v22
	global_store_dwordx2 v[28:29], v[20:21], off offset:192
	v_mov_b64_e32 v[20:21], v[12:13]
	v_lshlrev_b32_e32 v22, 16, v20
	v_mul_f32_e32 v24, 0xbfb8aa3b, v22
	v_exp_f32_e32 v24, v24
	v_and_b32_e32 v20, 0xffff0000, v20
	v_lshlrev_b32_e32 v23, 16, v21
	v_and_b32_e32 v21, 0xffff0000, v21
	v_add_f32_e32 v24, 1.0, v24
	s_nop 0
	v_rcp_f32_e32 v25, v24
	s_nop 0
	v_mul_f32_e32 v22, v22, v25
	v_mul_f32_e32 v16, v16, v22
	v_mul_f32_e32 v22, 0xbfb8aa3b, v20
	v_exp_f32_e32 v22, v22
	s_nop 0
	v_add_f32_e32 v22, 1.0, v22
	s_nop 0
	v_rcp_f32_e32 v24, v22
	s_nop 0
	v_mul_f32_e32 v20, v20, v24
	v_mul_f32_e32 v17, v17, v20
	v_cvt_pk_bf16_f32 v16, v16, v17
	v_mul_f32_e32 v17, v18, v32
	v_mul_f32_e32 v18, 0xbfb8aa3b, v23
	v_exp_f32_e32 v18, v18
	s_nop 0
	v_add_f32_e32 v18, 1.0, v18
	s_nop 0
	v_rcp_f32_e32 v20, v18
	s_nop 0
	v_mul_f32_e32 v18, v23, v20
	v_mul_f32_e32 v17, v17, v18
	v_mul_f32_e32 v18, v19, v32
	v_mul_f32_e32 v19, 0xbfb8aa3b, v21
	v_exp_f32_e32 v19, v19
	s_nop 0
	v_add_f32_e32 v19, 1.0, v19
	s_nop 0
	v_rcp_f32_e32 v20, v19
	s_nop 0
	v_mul_f32_e32 v19, v21, v20
	v_mul_f32_e32 v18, v18, v19
	v_cvt_pk_bf16_f32 v17, v17, v18
	global_store_dwordx2 v[28:29], v[16:17], off offset:224

.LBB0_503:
	v_mad_i64_i32 v[4:5], s[0:1], v82, s15, v[8:9]
	v_lshlrev_b64 v[4:5], 1, v[4:5]
	v_lshl_add_u64 v[14:15], s[10:11], 0, v[4:5]
	v_lshl_add_u64 v[4:5], s[12:13], 0, v[4:5]
	global_load_dwordx2 v[16:17], v[14:15], off nt
	global_load_dwordx2 v[22:23], v[4:5], off nt
	v_mov_b64_e32 v[6:7], s[76:77]
	v_mad_i64_i32 v[6:7], s[0:1], v82, s69, v[6:7]
	v_lshlrev_b32_e32 v144, 1, v8
	v_lshl_add_u64 v[6:7], v[6:7], 0, v[144:145]
	s_mov_b64 s[0:1], 0xb9a3000
	v_lshl_add_u64 v[12:13], v[6:7], 0, s[0:1]
	v_add_co_u32_e32 v6, vcc, 0xb9a3000, v6
	s_nop 1
	v_addc_co_u32_e32 v7, vcc, 0, v7, vcc
	global_load_dwordx2 v[34:35], v[6:7], off nt
	global_load_dwordx2 v[24:25], v[14:15], off offset:512 nt
	global_load_dwordx2 v[26:27], v[4:5], off offset:512 nt
	global_load_dwordx2 v[76:77], v[12:13], off offset:512 nt
	global_load_dwordx2 v[28:29], v[14:15], off offset:1024 nt
	global_load_dwordx2 v[30:31], v[4:5], off offset:1024 nt
	global_load_dwordx2 v[62:63], v[12:13], off offset:1024 nt
	global_load_dwordx2 v[32:33], v[14:15], off offset:1536 nt
	global_load_dwordx2 v[38:39], v[4:5], off offset:1536 nt
	global_load_dwordx2 v[56:57], v[12:13], off offset:1536 nt
	global_load_dwordx2 v[40:41], v[14:15], off offset:2048 nt
	global_load_dwordx2 v[46:47], v[4:5], off offset:2048 nt
	global_load_dwordx2 v[42:43], v[12:13], off offset:2048 nt
	global_load_dwordx2 v[48:49], v[14:15], off offset:2560 nt
	global_load_dwordx2 v[50:51], v[4:5], off offset:2560 nt
	global_load_dwordx2 v[36:37], v[12:13], off offset:2560 nt
	global_load_dwordx2 v[52:53], v[14:15], off offset:3072 nt
	global_load_dwordx2 v[54:55], v[4:5], off offset:3072 nt
	global_load_dwordx2 v[20:21], v[12:13], off offset:3072 nt
	s_nop 0
	global_load_dwordx2 v[14:15], v[14:15], off offset:3584 nt
	s_nop 0
	global_load_dwordx2 v[68:69], v[4:5], off offset:3584 nt
	global_load_dwordx2 v[18:19], v[12:13], off offset:3584 nt
	s_waitcnt vmcnt(21)
	v_lshlrev_b32_e32 v98, 16, v34
	v_mul_f32_e32 v100, 0xbfb8aa3b, v98
	v_exp_f32_e32 v100, v100
	v_and_b32_e32 v34, 0xffff0000, v34
	v_lshlrev_b32_e32 v99, 16, v35
	v_and_b32_e32 v35, 0xffff0000, v35
	v_add_f32_e32 v100, 1.0, v100
	v_lshlrev_b32_e32 v4, 16, v16
	v_and_b32_e32 v5, 0xffff0000, v16
	v_lshlrev_b32_e32 v6, 16, v22
	v_and_b32_e32 v7, 0xffff0000, v22
	v_pk_add_f32 v[4:5], v[4:5], v[6:7]
	v_lshlrev_b32_e32 v6, 16, v17
	v_and_b32_e32 v7, 0xffff0000, v17
	v_lshlrev_b32_e32 v12, 16, v23
	v_and_b32_e32 v13, 0xffff0000, v23
	v_pk_add_f32 v[6:7], v[6:7], v[12:13]
	v_add_f32_e32 v12, v4, v5
	v_add_f32_e32 v12, v6, v12
	v_add_f32_e32 v70, v7, v12
	s_waitcnt vmcnt(20)
	v_lshlrev_b32_e32 v12, 16, v24
	v_and_b32_e32 v13, 0xffff0000, v24
	s_waitcnt vmcnt(19)
	v_lshlrev_b32_e32 v16, 16, v26
	v_and_b32_e32 v17, 0xffff0000, v26
	v_pk_add_f32 v[80:81], v[12:13], v[16:17]
	v_lshlrev_b32_e32 v12, 16, v25
	v_and_b32_e32 v13, 0xffff0000, v25
	v_lshlrev_b32_e32 v16, 16, v27
	v_and_b32_e32 v17, 0xffff0000, v27
	v_pk_add_f32 v[78:79], v[12:13], v[16:17]
	v_add_f32_e32 v12, v80, v81
	v_add_f32_e32 v12, v78, v12
	v_add_f32_e32 v26, v79, v12
	s_waitcnt vmcnt(17)
	v_lshlrev_b32_e32 v12, 16, v28
	v_and_b32_e32 v13, 0xffff0000, v28
	s_waitcnt vmcnt(16)
	v_lshlrev_b32_e32 v16, 16, v30
	v_and_b32_e32 v17, 0xffff0000, v30
	v_pk_add_f32 v[64:65], v[12:13], v[16:17]
	v_lshlrev_b32_e32 v12, 16, v29
	v_and_b32_e32 v13, 0xffff0000, v29
	v_lshlrev_b32_e32 v16, 16, v31
	v_and_b32_e32 v17, 0xffff0000, v31
	v_pk_add_f32 v[66:67], v[12:13], v[16:17]
	v_add_f32_e32 v12, v64, v65
	v_add_f32_e32 v12, v66, v12
	v_add_f32_e32 v27, v67, v12
	s_waitcnt vmcnt(14)
	v_lshlrev_b32_e32 v12, 16, v32
	v_and_b32_e32 v13, 0xffff0000, v32
	ds_bpermute_b32 v32, v84, v26
	s_waitcnt vmcnt(13)
	v_lshlrev_b32_e32 v16, 16, v38
	v_and_b32_e32 v17, 0xffff0000, v38
	v_pk_add_f32 v[60:61], v[12:13], v[16:17]
	v_lshlrev_b32_e32 v12, 16, v33
	s_waitcnt lgkmcnt(0)
	v_add_f32_e32 v26, v26, v32
	ds_bpermute_b32 v32, v84, v27
	v_and_b32_e32 v13, 0xffff0000, v33
	v_lshlrev_b32_e32 v16, 16, v39
	v_and_b32_e32 v17, 0xffff0000, v39
	v_pk_add_f32 v[58:59], v[12:13], v[16:17]
	v_add_f32_e32 v12, v60, v61
	v_add_f32_e32 v12, v58, v12
	v_add_f32_e32 v28, v59, v12
	s_waitcnt vmcnt(11)
	v_lshlrev_b32_e32 v12, 16, v40
	v_and_b32_e32 v13, 0xffff0000, v40
	s_waitcnt vmcnt(10)
	v_lshlrev_b32_e32 v16, 16, v46
	v_and_b32_e32 v17, 0xffff0000, v46
	s_waitcnt lgkmcnt(0)
	v_add_f32_e32 v27, v27, v32
	ds_bpermute_b32 v32, v84, v28
	v_pk_add_f32 v[44:45], v[12:13], v[16:17]
	v_lshlrev_b32_e32 v12, 16, v41
	v_and_b32_e32 v13, 0xffff0000, v41
	v_lshlrev_b32_e32 v16, 16, v47
	v_and_b32_e32 v17, 0xffff0000, v47
	v_pk_add_f32 v[46:47], v[12:13], v[16:17]
	v_add_f32_e32 v12, v44, v45
	v_add_f32_e32 v12, v46, v12
	v_add_f32_e32 v29, v47, v12
	s_waitcnt vmcnt(8)
	v_lshlrev_b32_e32 v12, 16, v48
	v_and_b32_e32 v13, 0xffff0000, v48
	s_waitcnt vmcnt(7)
	v_lshlrev_b32_e32 v16, 16, v50
	v_and_b32_e32 v17, 0xffff0000, v50
	s_waitcnt lgkmcnt(0)
	v_add_f32_e32 v28, v28, v32
	ds_bpermute_b32 v32, v84, v29
	v_pk_add_f32 v[40:41], v[12:13], v[16:17]
	v_lshlrev_b32_e32 v12, 16, v49
	v_and_b32_e32 v13, 0xffff0000, v49
	v_lshlrev_b32_e32 v16, 16, v51
	v_and_b32_e32 v17, 0xffff0000, v51
	v_pk_add_f32 v[38:39], v[12:13], v[16:17]
	v_add_f32_e32 v12, v40, v41
	v_add_f32_e32 v12, v38, v12
	v_add_f32_e32 v30, v39, v12
	s_waitcnt vmcnt(5)
	v_lshlrev_b32_e32 v12, 16, v52
	v_and_b32_e32 v13, 0xffff0000, v52
	s_waitcnt vmcnt(4)
	v_lshlrev_b32_e32 v16, 16, v54
	v_and_b32_e32 v17, 0xffff0000, v54
	s_waitcnt lgkmcnt(0)
	v_add_f32_e32 v29, v29, v32
	ds_bpermute_b32 v32, v84, v30
	v_pk_add_f32 v[22:23], v[12:13], v[16:17]
	v_lshlrev_b32_e32 v12, 16, v53
	v_and_b32_e32 v13, 0xffff0000, v53
	v_lshlrev_b32_e32 v16, 16, v55
	v_and_b32_e32 v17, 0xffff0000, v55
	v_pk_add_f32 v[24:25], v[12:13], v[16:17]
	v_add_f32_e32 v12, v22, v23
	v_add_f32_e32 v12, v24, v12
	v_add_f32_e32 v31, v25, v12
	s_waitcnt vmcnt(2)
	v_lshlrev_b32_e32 v12, 16, v14
	v_and_b32_e32 v13, 0xffff0000, v14
	s_waitcnt vmcnt(1)
	v_lshlrev_b32_e32 v16, 16, v68
	v_and_b32_e32 v17, 0xffff0000, v68
	s_waitcnt lgkmcnt(0)
	v_add_f32_e32 v30, v30, v32
	ds_bpermute_b32 v32, v84, v31
	v_pk_add_f32 v[16:17], v[12:13], v[16:17]
	v_lshlrev_b32_e32 v12, 16, v15
	v_and_b32_e32 v13, 0xffff0000, v15
	v_lshlrev_b32_e32 v14, 16, v69
	v_and_b32_e32 v15, 0xffff0000, v69
	v_pk_add_f32 v[14:15], v[12:13], v[14:15]
	v_add_f32_e32 v12, v16, v17
	v_add_f32_e32 v12, v14, v12
	v_add_f32_e32 v12, v15, v12
	ds_bpermute_b32 v13, v84, v70
	s_waitcnt lgkmcnt(1)
	v_add_f32_e32 v31, v31, v32
	ds_bpermute_b32 v32, v84, v12
	s_waitcnt lgkmcnt(1)
	v_add_f32_e32 v13, v70, v13
	s_waitcnt lgkmcnt(0)
	v_add_f32_e32 v12, v12, v32
	ds_bpermute_b32 v32, v85, v13
	s_waitcnt lgkmcnt(0)
	v_add_f32_e32 v13, v13, v32
	ds_bpermute_b32 v32, v85, v26
	s_waitcnt lgkmcnt(0)
	v_add_f32_e32 v26, v26, v32
	ds_bpermute_b32 v32, v85, v27
	v_rcp_f32_e32 v101, v100
	s_nop 0
	v_mul_f32_e32 v98, v98, v101
	v_mul_f32_e32 v100, 0xbfb8aa3b, v34
	v_exp_f32_e32 v100, v100
	s_waitcnt lgkmcnt(0)
	v_add_f32_e32 v27, v27, v32
	ds_bpermute_b32 v32, v85, v28
	v_add_f32_e32 v100, 1.0, v100
	s_waitcnt lgkmcnt(0)
	v_add_f32_e32 v28, v28, v32
	ds_bpermute_b32 v32, v85, v29
	s_waitcnt lgkmcnt(0)
	v_add_f32_e32 v29, v29, v32
	ds_bpermute_b32 v32, v85, v30
	s_waitcnt lgkmcnt(0)
	v_add_f32_e32 v30, v30, v32
	ds_bpermute_b32 v32, v85, v31
	s_waitcnt lgkmcnt(0)
	v_add_f32_e32 v31, v31, v32
	ds_bpermute_b32 v32, v85, v12
	v_rcp_f32_e32 v101, v100
	s_nop 0
	v_mul_f32_e32 v100, v34, v101
	v_mul_f32_e32 v34, 0xbfb8aa3b, v99
	v_exp_f32_e32 v34, v34
	s_waitcnt lgkmcnt(0)
	v_add_f32_e32 v12, v12, v32
	ds_bpermute_b32 v32, v86, v13
	v_add_f32_e32 v34, 1.0, v34
	s_waitcnt lgkmcnt(0)
	v_add_f32_e32 v13, v13, v32
	ds_bpermute_b32 v32, v86, v26
	s_waitcnt lgkmcnt(0)
	v_add_f32_e32 v26, v26, v32
	ds_bpermute_b32 v32, v86, v27
	s_waitcnt lgkmcnt(0)
	v_add_f32_e32 v27, v27, v32
	ds_bpermute_b32 v32, v86, v28
	s_waitcnt lgkmcnt(0)
	v_add_f32_e32 v28, v28, v32
	ds_bpermute_b32 v32, v86, v29
	v_rcp_f32_e32 v101, v34
	s_nop 0
	v_mul_f32_e32 v99, v99, v101
	v_mul_f32_e32 v34, 0xbfb8aa3b, v35
	v_exp_f32_e32 v34, v34
	s_waitcnt lgkmcnt(0)
	v_add_f32_e32 v29, v29, v32
	ds_bpermute_b32 v32, v86, v30
	v_add_f32_e32 v34, 1.0, v34
	s_waitcnt lgkmcnt(0)
	v_add_f32_e32 v30, v30, v32
	ds_bpermute_b32 v32, v86, v31
	s_waitcnt lgkmcnt(0)
	v_add_f32_e32 v31, v31, v32
	ds_bpermute_b32 v32, v86, v12
	s_waitcnt lgkmcnt(0)
	v_add_f32_e32 v12, v12, v32
	ds_bpermute_b32 v32, v87, v13
	s_waitcnt lgkmcnt(0)
	v_add_f32_e32 v13, v13, v32
	ds_bpermute_b32 v32, v87, v26
	v_rcp_f32_e32 v101, v34
	s_nop 0
	v_mul_f32_e32 v101, v35, v101
	s_waitcnt lgkmcnt(0)
	v_add_f32_e32 v26, v26, v32
	ds_bpermute_b32 v32, v87, v27
	s_waitcnt lgkmcnt(0)
	v_add_f32_e32 v27, v27, v32
	ds_bpermute_b32 v32, v87, v28
	s_waitcnt lgkmcnt(0)
	v_add_f32_e32 v28, v28, v32
	ds_bpermute_b32 v32, v87, v29
	s_waitcnt lgkmcnt(0)
	v_add_f32_e32 v29, v29, v32
	ds_bpermute_b32 v32, v87, v30
	s_waitcnt lgkmcnt(0)
	v_add_f32_e32 v30, v30, v32
	ds_bpermute_b32 v32, v87, v31
	s_waitcnt lgkmcnt(0)
	v_add_f32_e32 v31, v31, v32
	ds_bpermute_b32 v32, v87, v12
	s_waitcnt lgkmcnt(0)
	v_add_f32_e32 v12, v12, v32
	ds_bpermute_b32 v32, v88, v13
	s_waitcnt lgkmcnt(0)
	v_add_f32_e32 v13, v13, v32
	ds_bpermute_b32 v32, v88, v26
	s_waitcnt lgkmcnt(0)
	v_add_f32_e32 v26, v26, v32
	ds_bpermute_b32 v32, v88, v27
	s_waitcnt lgkmcnt(0)
	v_add_f32_e32 v27, v27, v32
	ds_bpermute_b32 v32, v88, v28
	s_waitcnt lgkmcnt(0)
	v_add_f32_e32 v28, v28, v32
	ds_bpermute_b32 v32, v88, v29
	s_waitcnt lgkmcnt(0)
	v_add_f32_e32 v29, v29, v32
	ds_bpermute_b32 v32, v88, v30
	s_waitcnt lgkmcnt(0)
	v_add_f32_e32 v30, v30, v32
	ds_bpermute_b32 v32, v88, v31
	s_waitcnt lgkmcnt(0)
	v_add_f32_e32 v31, v31, v32
	ds_bpermute_b32 v32, v88, v12
	s_waitcnt lgkmcnt(0)
	v_add_f32_e32 v12, v12, v32
	ds_bpermute_b32 v32, v89, v13
	s_waitcnt lgkmcnt(0)
	v_add_f32_e32 v13, v13, v32
	ds_bpermute_b32 v32, v89, v26
	v_fmamk_f32 v5, v13, 0xbb800000, v5
	v_fmac_f32_e32 v4, 0xbb800000, v13
	v_fmamk_f32 v7, v13, 0xbb800000, v7
	v_fmac_f32_e32 v6, 0xbb800000, v13
	s_waitcnt lgkmcnt(0)
	v_add_f32_e32 v26, v26, v32
	v_fmamk_f32 v81, v26, 0xbb800000, v81
	v_fmac_f32_e32 v80, 0xbb800000, v26
	v_pk_mul_f32 v[92:93], v[4:5], v[4:5]
	v_fmamk_f32 v79, v26, 0xbb800000, v79
	v_fmac_f32_e32 v78, 0xbb800000, v26
	v_pk_mul_f32 v[96:97], v[80:81], v[80:81]
	v_pk_mul_f32 v[90:91], v[6:7], v[6:7]
	v_pk_mul_f32 v[94:95], v[78:79], v[78:79]
	v_mov_b32_e32 v34, v96
	v_mov_b32_e32 v35, v92
	v_mov_b32_e32 v92, v97
	v_pk_add_f32 v[34:35], v[34:35], v[92:93]
	v_mov_b32_e32 v92, v94
	v_mov_b32_e32 v93, v90
	v_pk_add_f32 v[34:35], v[92:93], v[34:35]
	v_mov_b32_e32 v90, v95
	v_pk_add_f32 v[34:35], v[90:91], v[34:35]
	ds_bpermute_b32 v91, v84, v35
	ds_bpermute_b32 v90, v84, v34
	ds_bpermute_b32 v32, v89, v27
	s_waitcnt lgkmcnt(1)
	v_pk_add_f32 v[34:35], v[34:35], v[90:91]
	ds_bpermute_b32 v91, v85, v35
	ds_bpermute_b32 v90, v85, v34
	s_waitcnt lgkmcnt(2)
	v_add_f32_e32 v27, v27, v32
	ds_bpermute_b32 v32, v89, v28
	v_fmamk_f32 v65, v27, 0xbb800000, v65
	v_fmac_f32_e32 v64, 0xbb800000, v27
	s_waitcnt lgkmcnt(1)
	v_pk_add_f32 v[34:35], v[34:35], v[90:91]
	ds_bpermute_b32 v91, v86, v35
	s_waitcnt lgkmcnt(1)
	v_add_f32_e32 v28, v28, v32
	ds_bpermute_b32 v32, v89, v29
	ds_bpermute_b32 v90, v86, v34
	v_fmamk_f32 v61, v28, 0xbb800000, v61
	v_fmac_f32_e32 v60, 0xbb800000, v28
	v_fmamk_f32 v67, v27, 0xbb800000, v67
	s_waitcnt lgkmcnt(1)
	v_add_f32_e32 v29, v29, v32
	ds_bpermute_b32 v32, v89, v30
	s_waitcnt lgkmcnt(1)
	v_pk_add_f32 v[34:35], v[34:35], v[90:91]
	ds_bpermute_b32 v91, v87, v35
	ds_bpermute_b32 v90, v87, v34
	v_fmac_f32_e32 v66, 0xbb800000, v27
	s_waitcnt lgkmcnt(2)
	v_add_f32_e32 v30, v30, v32
	ds_bpermute_b32 v32, v89, v31
	v_pk_mul_f32 v[70:71], v[64:65], v[64:65]
	s_waitcnt lgkmcnt(1)
	v_pk_add_f32 v[34:35], v[34:35], v[90:91]
	ds_bpermute_b32 v91, v88, v35
	ds_bpermute_b32 v90, v88, v34
	s_waitcnt lgkmcnt(2)
	v_add_f32_e32 v31, v31, v32
	ds_bpermute_b32 v32, v89, v12
	v_fmamk_f32 v59, v28, 0xbb800000, v59
	v_fmac_f32_e32 v58, 0xbb800000, v28
	s_waitcnt lgkmcnt(1)
	v_pk_add_f32 v[34:35], v[34:35], v[90:91]
	ds_bpermute_b32 v91, v89, v35
	ds_bpermute_b32 v90, v89, v34
	s_waitcnt lgkmcnt(2)
	v_add_f32_e32 v12, v12, v32
	v_fmamk_f32 v17, v12, 0xbb800000, v17
	v_fmac_f32_e32 v16, 0xbb800000, v12
	v_fmamk_f32 v15, v12, 0xbb800000, v15
	v_fmac_f32_e32 v14, 0xbb800000, v12
	v_mad_i64_i32 v[12:13], s[0:1], v82, s70, v[10:11]
	s_mov_b32 s0, 0x358637bd
	s_waitcnt lgkmcnt(0)
	v_pk_add_f32 v[90:91], v[34:35], v[90:91]
	v_mov_b64_e32 v[34:35], s[0:1]
	v_pk_fma_f32 v[90:91], v[90:91], s[34:35], v[34:35] op_sel_hi:[1,0,0]
	v_pk_mul_f32 v[74:75], v[60:61], v[60:61]
	v_mul_f32_e32 v92, 0x4b800000, v91
	v_cmp_gt_f32_e64 s[0:1], s72, v91
	v_cmp_gt_f32_e32 vcc, s72, v90
	v_pk_mul_f32 v[68:69], v[66:67], v[66:67]
	v_cndmask_b32_e64 v91, v91, v92, s[0:1]
	v_rsq_f32_e32 v91, v91
	v_pk_mul_f32 v[72:73], v[58:59], v[58:59]
	v_fmamk_f32 v45, v29, 0xbb800000, v45
	v_fmac_f32_e32 v44, 0xbb800000, v29
	v_mul_f32_e32 v92, 0x45800000, v91
	v_cndmask_b32_e64 v91, v91, v92, s[0:1]
	v_mul_f32_e32 v4, v4, v91
	v_mul_f32_e32 v5, v5, v91
	v_mul_f32_e32 v4, v0, v4
	v_mul_f32_e32 v5, v1, v5
	v_mul_f32_e32 v4, v98, v4
	v_mul_f32_e32 v5, v100, v5
	v_cvt_pk_bf16_f32 v4, v4, v5
	v_mul_f32_e32 v5, v6, v91
	v_mul_f32_e32 v5, v2, v5
	v_mul_f32_e32 v6, v7, v91
	v_mul_f32_e32 v5, v99, v5
	v_mul_f32_e32 v6, v3, v6
	v_mul_f32_e32 v6, v101, v6
	v_cvt_pk_bf16_f32 v5, v5, v6
	global_store_dwordx2 v[12:13], v[4:5], off
	v_mul_f32_e32 v4, 0x4b800000, v90
	v_cndmask_b32_e32 v4, v90, v4, vcc
	v_rsq_f32_e32 v4, v4
	v_lshlrev_b32_e32 v91, 16, v76
	v_and_b32_e32 v76, 0xffff0000, v76
	v_lshlrev_b32_e32 v92, 16, v77
	v_mul_f32_e32 v5, 0x45800000, v4
	v_cndmask_b32_e32 v90, v4, v5, vcc
	ds_read_b128 v[4:7], v83 offset:1024
	v_mul_f32_e32 v80, v80, v90
	v_and_b32_e32 v77, 0xffff0000, v77
	v_fmamk_f32 v41, v30, 0xbb800000, v41
	v_fmac_f32_e32 v40, 0xbb800000, v30
	s_waitcnt lgkmcnt(0)
	v_mul_f32_e32 v4, v80, v4
	v_mul_f32_e32 v80, 0xbfb8aa3b, v91
	v_exp_f32_e32 v80, v80
	v_fmamk_f32 v47, v29, 0xbb800000, v47
	v_fmac_f32_e32 v46, 0xbb800000, v29
	v_pk_mul_f32 v[50:51], v[44:45], v[44:45]
	v_add_f32_e32 v80, 1.0, v80
	v_fmamk_f32 v39, v30, 0xbb800000, v39
	v_fmac_f32_e32 v38, 0xbb800000, v30
	v_pk_mul_f32 v[54:55], v[40:41], v[40:41]
	v_rcp_f32_e32 v93, v80
	s_nop 0
	v_mul_f32_e32 v80, v91, v93
	v_mul_f32_e32 v4, v80, v4
	v_mul_f32_e32 v80, v81, v90
	v_mul_f32_e32 v5, v80, v5
	v_mul_f32_e32 v80, 0xbfb8aa3b, v76
	v_exp_f32_e32 v80, v80
	v_pk_mul_f32 v[48:49], v[46:47], v[46:47]
	v_pk_mul_f32 v[52:53], v[38:39], v[38:39]
	v_fmamk_f32 v23, v31, 0xbb800000, v23
	v_add_f32_e32 v80, 1.0, v80
	v_fmac_f32_e32 v22, 0xbb800000, v31
	v_fmamk_f32 v25, v31, 0xbb800000, v25
	v_fmac_f32_e32 v24, 0xbb800000, v31
	v_rcp_f32_e32 v81, v80
	s_nop 0
	v_mul_f32_e32 v76, v76, v81
	v_mul_f32_e32 v5, v76, v5
	v_cvt_pk_bf16_f32 v4, v4, v5
	v_mul_f32_e32 v5, v78, v90
	v_mul_f32_e32 v5, v5, v6
	v_mul_f32_e32 v6, 0xbfb8aa3b, v92
	v_exp_f32_e32 v6, v6
	v_pk_mul_f32 v[28:29], v[22:23], v[22:23]
	v_pk_mul_f32 v[32:33], v[16:17], v[16:17]
	v_pk_mul_f32 v[26:27], v[24:25], v[24:25]
	v_add_f32_e32 v6, 1.0, v6
	v_pk_mul_f32 v[30:31], v[14:15], v[14:15]
	v_add_u32_e32 v82, s14, v82
	v_rcp_f32_e32 v76, v6
	s_nop 0
	v_mul_f32_e32 v6, v92, v76
	v_mul_f32_e32 v5, v6, v5
	v_mul_f32_e32 v6, v79, v90
	v_mul_f32_e32 v6, v6, v7
	v_mul_f32_e32 v7, 0xbfb8aa3b, v77
	v_exp_f32_e32 v7, v7
	s_nop 0
	v_add_f32_e32 v7, 1.0, v7
	s_nop 0
	v_rcp_f32_e32 v76, v7
	s_nop 0
	v_mul_f32_e32 v7, v77, v76
	v_lshlrev_b32_e32 v76, 16, v62
	v_mul_f32_e32 v78, 0xbfb8aa3b, v76
	v_exp_f32_e32 v78, v78
	v_and_b32_e32 v62, 0xffff0000, v62
	v_lshlrev_b32_e32 v77, 16, v63
	v_and_b32_e32 v63, 0xffff0000, v63
	v_add_f32_e32 v78, 1.0, v78
	v_mul_f32_e32 v6, v7, v6
	v_cvt_pk_bf16_f32 v5, v5, v6
	global_store_dwordx2 v[12:13], v[4:5], off offset:512
	v_rcp_f32_e32 v79, v78
	s_nop 0
	v_mul_f32_e32 v76, v76, v79
	v_mul_f32_e32 v78, 0xbfb8aa3b, v62
	v_exp_f32_e32 v78, v78
	ds_read_b128 v[4:7], v83 offset:2048
	v_add_f32_e32 v78, 1.0, v78
	s_nop 0
	v_rcp_f32_e32 v79, v78
	s_nop 0
	v_mul_f32_e32 v78, v62, v79
	v_mul_f32_e32 v62, 0xbfb8aa3b, v77
	v_exp_f32_e32 v62, v62
	s_nop 0
	v_add_f32_e32 v62, 1.0, v62
	s_nop 0
	v_rcp_f32_e32 v79, v62
	s_nop 0
	v_mul_f32_e32 v77, v77, v79
	v_mul_f32_e32 v62, 0xbfb8aa3b, v63
	v_exp_f32_e32 v62, v62
	s_nop 0
	v_add_f32_e32 v62, 1.0, v62
	s_nop 0
	v_rcp_f32_e32 v79, v62
	s_nop 0
	v_mul_f32_e32 v79, v63, v79
	v_mov_b32_e32 v62, v74
	v_mov_b32_e32 v63, v70
	v_mov_b32_e32 v70, v75
	v_pk_add_f32 v[62:63], v[62:63], v[70:71]
	v_mov_b32_e32 v70, v72
	v_mov_b32_e32 v71, v68
	v_pk_add_f32 v[62:63], v[70:71], v[62:63]
	v_mov_b32_e32 v68, v73
	v_pk_add_f32 v[62:63], v[68:69], v[62:63]
	ds_bpermute_b32 v69, v84, v63
	ds_bpermute_b32 v68, v84, v62
	s_waitcnt lgkmcnt(0)
	v_pk_add_f32 v[62:63], v[62:63], v[68:69]
	ds_bpermute_b32 v69, v85, v63
	ds_bpermute_b32 v68, v85, v62
	s_waitcnt lgkmcnt(0)
	v_pk_add_f32 v[62:63], v[62:63], v[68:69]
	ds_bpermute_b32 v69, v86, v63
	ds_bpermute_b32 v68, v86, v62
	s_waitcnt lgkmcnt(0)
	v_pk_add_f32 v[62:63], v[62:63], v[68:69]
	ds_bpermute_b32 v69, v87, v63
	ds_bpermute_b32 v68, v87, v62
	s_waitcnt lgkmcnt(0)
	v_pk_add_f32 v[62:63], v[62:63], v[68:69]
	ds_bpermute_b32 v69, v88, v63
	ds_bpermute_b32 v68, v88, v62
	s_waitcnt lgkmcnt(0)
	v_pk_add_f32 v[62:63], v[62:63], v[68:69]
	ds_bpermute_b32 v69, v89, v63
	ds_bpermute_b32 v68, v89, v62
	s_waitcnt lgkmcnt(0)
	v_pk_add_f32 v[62:63], v[62:63], v[68:69]
	s_nop 0
	v_pk_fma_f32 v[62:63], v[62:63], s[34:35], v[34:35] op_sel_hi:[1,0,0]
	s_nop 0
	v_mul_f32_e32 v68, 0x4b800000, v63
	v_cmp_gt_f32_e64 s[0:1], s72, v63
	v_cmp_gt_f32_e32 vcc, s72, v62
	s_nop 0
	v_cndmask_b32_e64 v63, v63, v68, s[0:1]
	v_rsq_f32_e32 v63, v63
	s_nop 0
	v_mul_f32_e32 v68, 0x45800000, v63
	v_cndmask_b32_e64 v63, v63, v68, s[0:1]
	v_mul_f32_e32 v64, v64, v63
	v_mul_f32_e32 v4, v64, v4
	v_mul_f32_e32 v64, v65, v63
	v_mul_f32_e32 v5, v64, v5
	v_mul_f32_e32 v4, v76, v4
	v_mul_f32_e32 v5, v78, v5
	v_cvt_pk_bf16_f32 v4, v4, v5
	v_mul_f32_e32 v5, v66, v63
	v_mul_f32_e32 v5, v5, v6
	v_mul_f32_e32 v6, v67, v63
	v_mul_f32_e32 v5, v77, v5
	v_mul_f32_e32 v6, v6, v7
	v_mul_f32_e32 v6, v79, v6
	v_cvt_pk_bf16_f32 v5, v5, v6
	global_store_dwordx2 v[12:13], v[4:5], off offset:1024
	v_mul_f32_e32 v4, 0x4b800000, v62
	v_cndmask_b32_e32 v4, v62, v4, vcc
	v_rsq_f32_e32 v4, v4
	v_lshlrev_b32_e32 v63, 16, v56
	v_and_b32_e32 v56, 0xffff0000, v56
	v_lshlrev_b32_e32 v64, 16, v57
	v_mul_f32_e32 v5, 0x45800000, v4
	v_cndmask_b32_e32 v62, v4, v5, vcc
	ds_read_b128 v[4:7], v83 offset:3072
	v_mul_f32_e32 v60, v60, v62
	v_and_b32_e32 v57, 0xffff0000, v57
	s_waitcnt lgkmcnt(0)
	v_mul_f32_e32 v4, v60, v4
	v_mul_f32_e32 v60, 0xbfb8aa3b, v63
	v_exp_f32_e32 v60, v60
	s_nop 0
	v_add_f32_e32 v60, 1.0, v60
	s_nop 0
	v_rcp_f32_e32 v65, v60
	s_nop 0
	v_mul_f32_e32 v60, v63, v65
	v_mul_f32_e32 v4, v60, v4
	v_mul_f32_e32 v60, v61, v62
	v_mul_f32_e32 v5, v60, v5
	v_mul_f32_e32 v60, 0xbfb8aa3b, v56
	v_exp_f32_e32 v60, v60
	s_nop 0
	v_add_f32_e32 v60, 1.0, v60
	s_nop 0
	v_rcp_f32_e32 v61, v60
	s_nop 0
	v_mul_f32_e32 v56, v56, v61
	v_mul_f32_e32 v5, v56, v5
	v_cvt_pk_bf16_f32 v4, v4, v5
	v_mul_f32_e32 v5, v58, v62
	v_mul_f32_e32 v5, v5, v6
	v_mul_f32_e32 v6, 0xbfb8aa3b, v64
	v_exp_f32_e32 v6, v6
	s_nop 0
	v_add_f32_e32 v6, 1.0, v6
	s_nop 0
	v_rcp_f32_e32 v56, v6
	s_nop 0
	v_mul_f32_e32 v6, v64, v56
	v_mul_f32_e32 v5, v6, v5
	v_mul_f32_e32 v6, v59, v62
	v_mul_f32_e32 v6, v6, v7
	v_mul_f32_e32 v7, 0xbfb8aa3b, v57
	v_exp_f32_e32 v7, v7
	s_nop 0
	v_add_f32_e32 v7, 1.0, v7
	s_nop 0
	v_rcp_f32_e32 v56, v7
	s_nop 0
	v_mul_f32_e32 v7, v57, v56
	v_lshlrev_b32_e32 v56, 16, v42
	v_mul_f32_e32 v58, 0xbfb8aa3b, v56
	v_exp_f32_e32 v58, v58
	v_and_b32_e32 v42, 0xffff0000, v42
	v_lshlrev_b32_e32 v57, 16, v43
	v_and_b32_e32 v43, 0xffff0000, v43
	v_add_f32_e32 v58, 1.0, v58
	v_mul_f32_e32 v6, v7, v6
	v_cvt_pk_bf16_f32 v5, v5, v6
	global_store_dwordx2 v[12:13], v[4:5], off offset:1536
	v_rcp_f32_e32 v59, v58
	s_nop 0
	v_mul_f32_e32 v56, v56, v59
	v_mul_f32_e32 v58, 0xbfb8aa3b, v42
	v_exp_f32_e32 v58, v58
	ds_read_b128 v[4:7], v83 offset:4096
	v_add_f32_e32 v58, 1.0, v58
	s_nop 0
	v_rcp_f32_e32 v59, v58
	s_nop 0
	v_mul_f32_e32 v58, v42, v59
	v_mul_f32_e32 v42, 0xbfb8aa3b, v57
	v_exp_f32_e32 v42, v42
	s_nop 0
	v_add_f32_e32 v42, 1.0, v42
	s_nop 0
	v_rcp_f32_e32 v59, v42
	s_nop 0
	v_mul_f32_e32 v57, v57, v59
	v_mul_f32_e32 v42, 0xbfb8aa3b, v43
	v_exp_f32_e32 v42, v42
	s_nop 0
	v_add_f32_e32 v42, 1.0, v42
	s_nop 0
	v_rcp_f32_e32 v59, v42
	s_nop 0
	v_mul_f32_e32 v59, v43, v59
	v_mov_b32_e32 v42, v54
	v_mov_b32_e32 v43, v50
	v_mov_b32_e32 v50, v55
	v_pk_add_f32 v[42:43], v[42:43], v[50:51]
	v_mov_b32_e32 v50, v52
	v_mov_b32_e32 v51, v48
	v_pk_add_f32 v[42:43], v[50:51], v[42:43]
	v_mov_b32_e32 v48, v53
	v_pk_add_f32 v[42:43], v[48:49], v[42:43]
	ds_bpermute_b32 v49, v84, v43
	ds_bpermute_b32 v48, v84, v42
	s_waitcnt lgkmcnt(0)
	v_pk_add_f32 v[42:43], v[42:43], v[48:49]
	ds_bpermute_b32 v49, v85, v43
	ds_bpermute_b32 v48, v85, v42
	s_waitcnt lgkmcnt(0)
	v_pk_add_f32 v[42:43], v[42:43], v[48:49]
	ds_bpermute_b32 v49, v86, v43
	ds_bpermute_b32 v48, v86, v42
	s_waitcnt lgkmcnt(0)
	v_pk_add_f32 v[42:43], v[42:43], v[48:49]
	ds_bpermute_b32 v49, v87, v43
	ds_bpermute_b32 v48, v87, v42
	s_waitcnt lgkmcnt(0)
	v_pk_add_f32 v[42:43], v[42:43], v[48:49]
	ds_bpermute_b32 v49, v88, v43
	ds_bpermute_b32 v48, v88, v42
	s_waitcnt lgkmcnt(0)
	v_pk_add_f32 v[42:43], v[42:43], v[48:49]
	ds_bpermute_b32 v49, v89, v43
	ds_bpermute_b32 v48, v89, v42
	s_waitcnt lgkmcnt(0)
	v_pk_add_f32 v[42:43], v[42:43], v[48:49]
	s_nop 0
	v_pk_fma_f32 v[42:43], v[42:43], s[34:35], v[34:35] op_sel_hi:[1,0,0]
	s_nop 0
	v_mul_f32_e32 v48, 0x4b800000, v43
	v_cmp_gt_f32_e64 s[0:1], s72, v43
	v_cmp_gt_f32_e32 vcc, s72, v42
	s_nop 0
	v_cndmask_b32_e64 v43, v43, v48, s[0:1]
	v_rsq_f32_e32 v43, v43
	s_nop 0
	v_mul_f32_e32 v48, 0x45800000, v43
	v_cndmask_b32_e64 v43, v43, v48, s[0:1]
	v_mul_f32_e32 v44, v44, v43
	v_mul_f32_e32 v4, v44, v4
	v_mul_f32_e32 v44, v45, v43
	v_mul_f32_e32 v5, v44, v5
	v_mul_f32_e32 v4, v56, v4
	v_mul_f32_e32 v5, v58, v5
	v_cvt_pk_bf16_f32 v4, v4, v5
	v_mul_f32_e32 v5, v46, v43
	v_mul_f32_e32 v5, v5, v6
	v_mul_f32_e32 v6, v47, v43
	v_mul_f32_e32 v5, v57, v5
	v_mul_f32_e32 v6, v6, v7
	v_mul_f32_e32 v6, v59, v6
	v_cvt_pk_bf16_f32 v5, v5, v6
	global_store_dwordx2 v[12:13], v[4:5], off offset:2048
	v_mul_f32_e32 v4, 0x4b800000, v42
	v_cndmask_b32_e32 v4, v42, v4, vcc
	v_rsq_f32_e32 v4, v4
	v_lshlrev_b32_e32 v43, 16, v36
	v_and_b32_e32 v36, 0xffff0000, v36
	v_lshlrev_b32_e32 v44, 16, v37
	v_mul_f32_e32 v5, 0x45800000, v4
	v_cndmask_b32_e32 v42, v4, v5, vcc
	ds_read_b128 v[4:7], v83 offset:5120
	v_mul_f32_e32 v40, v40, v42
	v_and_b32_e32 v37, 0xffff0000, v37
	s_waitcnt lgkmcnt(0)
	v_mul_f32_e32 v4, v40, v4
	v_mul_f32_e32 v40, 0xbfb8aa3b, v43
	v_exp_f32_e32 v40, v40
	s_nop 0
	v_add_f32_e32 v40, 1.0, v40
	s_nop 0
	v_rcp_f32_e32 v45, v40
	s_nop 0
	v_mul_f32_e32 v40, v43, v45
	v_mul_f32_e32 v4, v40, v4
	v_mul_f32_e32 v40, v41, v42
	v_mul_f32_e32 v5, v40, v5
	v_mul_f32_e32 v40, 0xbfb8aa3b, v36
	v_exp_f32_e32 v40, v40
	s_nop 0
	v_add_f32_e32 v40, 1.0, v40
	s_nop 0
	v_rcp_f32_e32 v41, v40
	s_nop 0
	v_mul_f32_e32 v36, v36, v41
	v_mul_f32_e32 v5, v36, v5
	v_cvt_pk_bf16_f32 v4, v4, v5
	v_mul_f32_e32 v5, v38, v42
	v_mul_f32_e32 v5, v5, v6
	v_mul_f32_e32 v6, 0xbfb8aa3b, v44
	v_exp_f32_e32 v6, v6
	s_nop 0
	v_add_f32_e32 v6, 1.0, v6
	s_nop 0
	v_rcp_f32_e32 v36, v6
	s_nop 0
	v_mul_f32_e32 v6, v44, v36
	v_mul_f32_e32 v5, v6, v5
	v_mul_f32_e32 v6, v39, v42
	v_mul_f32_e32 v6, v6, v7
	v_mul_f32_e32 v7, 0xbfb8aa3b, v37
	v_exp_f32_e32 v7, v7
	s_nop 0
	v_add_f32_e32 v7, 1.0, v7
	s_nop 0
	v_rcp_f32_e32 v36, v7
	s_nop 0
	v_mul_f32_e32 v7, v37, v36
	v_lshlrev_b32_e32 v36, 16, v20
	v_mul_f32_e32 v38, 0xbfb8aa3b, v36
	v_exp_f32_e32 v38, v38
	v_and_b32_e32 v20, 0xffff0000, v20
	v_lshlrev_b32_e32 v37, 16, v21
	v_and_b32_e32 v21, 0xffff0000, v21
	v_add_f32_e32 v38, 1.0, v38
	v_mul_f32_e32 v6, v7, v6
	v_cvt_pk_bf16_f32 v5, v5, v6
	global_store_dwordx2 v[12:13], v[4:5], off offset:2560
	v_rcp_f32_e32 v39, v38
	s_nop 0
	v_mul_f32_e32 v36, v36, v39
	v_mul_f32_e32 v38, 0xbfb8aa3b, v20
	v_exp_f32_e32 v38, v38
	ds_read_b128 v[4:7], v83 offset:6144
	v_add_f32_e32 v38, 1.0, v38
	s_nop 0
	v_rcp_f32_e32 v39, v38
	s_nop 0
	v_mul_f32_e32 v38, v20, v39
	v_mul_f32_e32 v20, 0xbfb8aa3b, v37
	v_exp_f32_e32 v20, v20
	s_nop 0
	v_add_f32_e32 v20, 1.0, v20
	s_nop 0
	v_rcp_f32_e32 v39, v20
	s_nop 0
	v_mul_f32_e32 v37, v37, v39
	v_mul_f32_e32 v20, 0xbfb8aa3b, v21
	v_exp_f32_e32 v20, v20
	s_nop 0
	v_add_f32_e32 v20, 1.0, v20
	s_nop 0
	v_rcp_f32_e32 v39, v20
	s_nop 0
	v_mul_f32_e32 v39, v21, v39
	v_mov_b32_e32 v20, v32
	v_mov_b32_e32 v21, v28
	v_mov_b32_e32 v28, v33
	v_pk_add_f32 v[20:21], v[20:21], v[28:29]
	v_mov_b32_e32 v28, v30
	v_mov_b32_e32 v29, v26
	v_pk_add_f32 v[20:21], v[28:29], v[20:21]
	v_mov_b32_e32 v26, v31
	v_pk_add_f32 v[20:21], v[26:27], v[20:21]
	ds_bpermute_b32 v27, v84, v21
	ds_bpermute_b32 v26, v84, v20
	s_waitcnt lgkmcnt(0)
	v_pk_add_f32 v[20:21], v[20:21], v[26:27]
	ds_bpermute_b32 v27, v85, v21
	ds_bpermute_b32 v26, v85, v20
	s_waitcnt lgkmcnt(0)
	v_pk_add_f32 v[20:21], v[20:21], v[26:27]
	ds_bpermute_b32 v27, v86, v21
	ds_bpermute_b32 v26, v86, v20
	s_waitcnt lgkmcnt(0)
	v_pk_add_f32 v[20:21], v[20:21], v[26:27]
	ds_bpermute_b32 v27, v87, v21
	ds_bpermute_b32 v26, v87, v20
	s_waitcnt lgkmcnt(0)
	v_pk_add_f32 v[20:21], v[20:21], v[26:27]
	ds_bpermute_b32 v27, v88, v21
	ds_bpermute_b32 v26, v88, v20
	s_waitcnt lgkmcnt(0)
	v_pk_add_f32 v[20:21], v[20:21], v[26:27]
	ds_bpermute_b32 v27, v89, v21
	ds_bpermute_b32 v26, v89, v20
	s_waitcnt lgkmcnt(0)
	v_pk_add_f32 v[20:21], v[20:21], v[26:27]
	s_nop 0
	v_pk_fma_f32 v[20:21], v[20:21], s[34:35], v[34:35] op_sel_hi:[1,0,0]
	s_nop 0
	v_mul_f32_e32 v26, 0x4b800000, v21
	v_cmp_gt_f32_e64 s[0:1], s72, v21
	v_cmp_gt_f32_e32 vcc, s72, v20
	s_nop 0
	v_cndmask_b32_e64 v21, v21, v26, s[0:1]
	v_rsq_f32_e32 v21, v21
	s_nop 0
	v_mul_f32_e32 v26, 0x45800000, v21
	v_cndmask_b32_e64 v21, v21, v26, s[0:1]
	v_mul_f32_e32 v22, v22, v21
	v_mul_f32_e32 v4, v22, v4
	v_mul_f32_e32 v22, v23, v21
	v_mul_f32_e32 v5, v22, v5
	v_mul_f32_e32 v4, v36, v4
	v_mul_f32_e32 v5, v38, v5
	v_cvt_pk_bf16_f32 v4, v4, v5
	v_mul_f32_e32 v5, v24, v21
	v_mul_f32_e32 v5, v5, v6
	v_mul_f32_e32 v6, v25, v21
	v_mul_f32_e32 v5, v37, v5
	v_mul_f32_e32 v6, v6, v7
	v_mul_f32_e32 v6, v39, v6
	v_cvt_pk_bf16_f32 v5, v5, v6
	global_store_dwordx2 v[12:13], v[4:5], off offset:3072
	v_mul_f32_e32 v4, 0x4b800000, v20
	v_cndmask_b32_e32 v4, v20, v4, vcc
	v_rsq_f32_e32 v4, v4
	s_waitcnt vmcnt(7)
	v_lshlrev_b32_e32 v21, 16, v18
	v_and_b32_e32 v22, 0xffff0000, v18
	v_lshlrev_b32_e32 v23, 16, v19
	v_mul_f32_e32 v5, 0x45800000, v4
	v_cndmask_b32_e32 v20, v4, v5, vcc
	ds_read_b128 v[4:7], v83 offset:7168
	v_mul_f32_e32 v16, v16, v20
	v_and_b32_e32 v18, 0xffff0000, v19
	s_waitcnt lgkmcnt(0)
	v_mul_f32_e32 v4, v16, v4
	v_mul_f32_e32 v16, 0xbfb8aa3b, v21
	v_exp_f32_e32 v16, v16
	s_nop 0
	v_add_f32_e32 v16, 1.0, v16
	s_nop 0
	v_rcp_f32_e32 v19, v16
	s_nop 0
	v_mul_f32_e32 v16, v21, v19
	v_mul_f32_e32 v4, v16, v4
	v_mul_f32_e32 v16, v17, v20
	v_mul_f32_e32 v5, v16, v5
	v_mul_f32_e32 v16, 0xbfb8aa3b, v22
	v_exp_f32_e32 v16, v16
	s_nop 0
	v_add_f32_e32 v16, 1.0, v16
	s_nop 0
	v_rcp_f32_e32 v17, v16
	s_nop 0
	v_mul_f32_e32 v16, v22, v17
	v_mul_f32_e32 v5, v16, v5
	v_cvt_pk_bf16_f32 v4, v4, v5
	v_mul_f32_e32 v5, v14, v20
	v_mul_f32_e32 v5, v5, v6
	v_mul_f32_e32 v6, 0xbfb8aa3b, v23
	v_exp_f32_e32 v6, v6
	s_nop 0
	v_add_f32_e32 v6, 1.0, v6
	s_nop 0
	v_rcp_f32_e32 v14, v6
	s_nop 0
	v_mul_f32_e32 v6, v23, v14
	v_mul_f32_e32 v5, v6, v5
	v_mul_f32_e32 v6, v15, v20
	v_mul_f32_e32 v6, v6, v7
	v_mul_f32_e32 v7, 0xbfb8aa3b, v18
	v_exp_f32_e32 v7, v7
	s_nop 0
	v_add_f32_e32 v7, 1.0, v7
	s_movk_i32 s0, 0x1fff
	v_cmp_lt_i32_e32 vcc, s0, v82
	v_rcp_f32_e32 v14, v7
	s_nop 0
	v_mul_f32_e32 v7, v18, v14
	s_or_b64 s[6:7], vcc, s[6:7]
	v_mul_f32_e32 v6, v7, v6
	v_cvt_pk_bf16_f32 v5, v5, v6
	global_store_dwordx2 v[12:13], v[4:5], off offset:3584
	s_andn2_b64 exec, exec, s[6:7]
	s_cbranch_execnz .LBB0_503
